# P7 epilogue de-serialised: the 8 rowsq loads of the fused norm scale are requested at the head of each tile (free VGPRs v226-233, v197) instead of load+vmcnt(0) at the epilogue head
# speedup vs baseline: 1.0005x; 1.0005x over previous
;     __device__ bool next(int i, Unit& u) const {
;         const long L = (long)i * G + c; if (L >= nwg) return false;
;         int wgid = (int)L; { const int q = nwg / NXCD, r = nwg % NXCD, xcd = wgid % NXCD, off = wgid / NXCD; wgid = (xcd < r ? xcd * (q + 1) : r * (q + 1) + (xcd - r) * q) + off; }
;         const int nig = WGM * nN, gid = wgid / nig, fm = gid * WGM, gsz = (nM - fm) < WGM ? (nM - fm) : WGM;
;         u.pm = fm + ((wgid % nig) % gsz); u.pn = (wgid % nig) / gsz; u.ks = 0; u.koffA = 0; u.koffB = 0; return true;
;     __device__ __forceinline__ void operator()(const f32x4 (&acc)[2][2][4][2], const Unit& u, int wr, int wc, int fr, int fq) const {
;         const int row0 = u.pm * 256 + wr * 64 + fr, col0 = u.pn * 128 + wc * 32 + 8 * fq;
;         float rs[2][4];
; #pragma unroll
;         for (int ai = 0; ai < 2; ++ai)
; #pragma unroll
;             for (int m = 0; m < 4; ++m) rs[ai][m] = rowsq[row0 + ai * 128 + m * 16];
.LBB0_1202:
	v_lshl_add_u32 v226, s18, 8, v144
	v_ashrrev_i32_e32 v227, 31, v226
	v_lshl_add_u64 v[226:227], v[226:227], 2, s[96:97]
	global_load_dword v228, v[226:227], off
	global_load_dword v229, v[226:227], off offset:64
	global_load_dword v230, v[226:227], off offset:128
	global_load_dword v231, v[226:227], off offset:192
	global_load_dword v232, v[226:227], off offset:512
	global_load_dword v233, v[226:227], off offset:576
	global_load_dword v197, v[226:227], off offset:640
	global_load_dword v226, v[226:227], off offset:704
	s_nop 0
	s_nop 0
	s_nop 0
	s_nop 0
	s_nop 0
	s_nop 0
	s_nop 0
	s_nop 0
	s_nop 0
	s_nop 0
	s_nop 0
	s_nop 0
	s_nop 0
	s_nop 0
	s_nop 0
	s_nop 0
	s_nop 0
	s_nop 0
	s_nop 0
	s_nop 0
	s_nop 0
	s_nop 0
	s_nop 0
	s_nop 0
	s_nop 0
	s_nop 0
	s_nop 0
	s_nop 0
	s_nop 0
	s_nop 0
	s_nop 0
	s_nop 0
	s_nop 0
	s_nop 0
	s_nop 0
	s_nop 0
	s_nop 0
	s_nop 0
	s_nop 0
	s_nop 0
	s_nop 0
	s_nop 0
	s_nop 0
	s_add_i32 s31, s31, 1
	s_mul_i32 s0, s31, s35
	s_mul_hi_u32 s1, s31, s3
	s_add_i32 s1, s1, s0
	s_mul_i32 s0, s31, s3
	s_add_u32 s4, s0, s2
	s_addc_u32 s5, s1, s15
	v_cmp_gt_i64_e64 s[0:1], s[4:5], v[142:143]
	s_and_b64 vcc, exec, s[0:1]
	s_cbranch_vccnz .LBB0_1208
	s_ashr_i32 s8, s4, 31
	s_lshr_b32 s8, s8, 29
	s_add_i32 s10, s4, s8
	s_and_b32 s8, s10, -8
	s_sub_i32 s11, s4, s8
	s_cmp_gt_i32 s11, 3
	s_mov_b64 s[8:9], -1
	s_cbranch_scc0 .LBB0_1205
	s_mul_i32 s8, s11, 0xb5
	s_add_i32 s12, s8, 4
	s_mov_b64 s[8:9], 0

; #define PG8_STAGE(bufoff, gbase, voff) do { _Pragma("unroll") for (int _i = 0; _i < 2; ++_i) \
;         __builtin_amdgcn_global_load_lds((const unsigned*)((const char*)(gbase) + (voff)[_i]), (LAS unsigned*)(lds + (bufoff) + ldsw + _i * 8192), 16, 0, 0); } while (0)
; #define PG8_LDA(dst, b, h) do { _Pragma("unroll") for (int m = 0; m < 4; ++m) _Pragma("unroll") for (int k = 0; k < 2; ++k) dst[m][k] = *(const LAS bf16x8*)(lds + PG8_SA(b, h) + aoff + m * 2048 + k * 1024); } while (0)
; #define PG8_LDB(dst, b, h) do { _Pragma("unroll") for (int n = 0; n < 2; ++n) _Pragma("unroll") for (int k = 0; k < 2; ++k) dst[n][k] = *(const LAS bf16x8*)(lds + PG8_SB(b, h) + boff + n * 2048 + k * 1024); } while (0)
; #define PG8_MMA(ai, bj, At, Bt) do { __builtin_amdgcn_s_setprio(1); _Pragma("unroll") for (int m = 0; m < 4; ++m) _Pragma("unroll") for (int n = 0; n < 2; ++n) _Pragma("unroll") for (int k = 0; k < 2; ++k) \
;         acc[ai][bj][m][n] = __builtin_amdgcn_mfma_f32_16x16x32_bf16(Bt[n][k], At[m][k], acc[ai][bj][m][n], 0, 0, 0); __builtin_amdgcn_s_setprio(0); } while (0)
; #define PG8_WAIT_V(n) asm volatile("s_waitcnt vmcnt(" #n ")" ::: "memory")
; #define PG8_WAIT_L(n) asm volatile("s_waitcnt lgkmcnt(" #n ")" ::: "memory")
; #define PG8_BAR __builtin_amdgcn_s_barrier()
; #define PG8_SCHED __builtin_amdgcn_sched_barrier(0)
; template <class Epi, class Sched>
; __device__ __forceinline__ void gemm_phase(LAS unsigned char* lds, const Gemm g, const Sched& S, const Epi& E) {
;     ...
;             PG8_LDB(B0, 0, 0); PG8_SCHED; PG8_LDA(At, 0, 0); PG8_STAGE(PG8_SA(1, 1), a1 + hstepA, voffA);
;             PG8_WAIT_L(8); PG8_BAR; PG8_WAIT_L(0); PG8_MMA(0, 0, At, B0); PG8_BAR; PG8_SCHED;
;             PG8_LDB(B1, 0, 1); PG8_STAGE(PG8_SB(0, 0), b2, voffB);
;             PG8_BAR; PG8_WAIT_L(0); PG8_MMA(0, 1, At, B1); PG8_BAR;
;             PG8_LDA(At, 0, 1); PG8_STAGE(PG8_SA(0, 0), a2, voffA);
;             PG8_BAR; PG8_WAIT_L(0); PG8_MMA(1, 0, At, B0); PG8_BAR; PG8_SCHED;
;             PG8_STAGE(PG8_SB(0, 1), b2 + hstepB, voffB);
;             PG8_WAIT_V(6); PG8_BAR; PG8_MMA(1, 1, At, B1); PG8_BAR;
.Lp7_prio_done:
.LBB0_1209:
	ds_read_b128 v[152:155], v147
	ds_read_b128 v[156:159], v147 offset:1024
	ds_read_b128 v[160:163], v147 offset:2048
	ds_read_b128 v[164:167], v147 offset:3072
	s_add_u32 s26, s24, 0xfff80080
	s_addc_u32 s27, s25, -1
	s_cmp_eq_u32 s45, 28
	s_cselect_b32 s37, s4, s27
	s_cselect_b32 s36, s5, s26
	s_cselect_b32 s27, s9, s44
	s_cselect_b32 s26, s11, s43
	v_lshl_add_u64 v[202:203], s[24:25], 0, v[136:137]
	s_add_i32 m0, s19, 0xc000
	ds_read_b128 v[168:171], v148
	ds_read_b128 v[172:175], v148 offset:1024
	ds_read_b128 v[176:179], v148 offset:2048
	ds_read_b128 v[180:183], v148 offset:3072
	ds_read_b128 v[184:187], v148 offset:4096
	ds_read_b128 v[188:191], v148 offset:5120
	ds_read_b128 v[192:195], v148 offset:6144
	ds_read_b128 v[198:201], v148 offset:7168
	global_load_lds_dwordx4 v[202:203], off
	v_lshl_add_u64 v[202:203], s[24:25], 0, v[138:139]
	s_add_i32 m0, s19, 0xe000
	s_nop 0
	global_load_lds_dwordx4 v[202:203], off
	s_waitcnt lgkmcnt(8)
	s_barrier
	s_waitcnt lgkmcnt(0)
	s_waitcnt lgkmcnt(0)
	v_mfma_f32_16x16x32_bf16 v[116:119], v[152:155], v[168:171], v[116:119]
	v_mfma_f32_16x16x32_bf16 v[112:115], v[160:163], v[168:171], v[112:115]
	v_mfma_f32_16x16x32_bf16 v[108:111], v[152:155], v[176:179], v[108:111]
	v_mfma_f32_16x16x32_bf16 v[100:103], v[160:163], v[176:179], v[100:103]
	v_mfma_f32_16x16x32_bf16 v[92:95], v[152:155], v[184:187], v[92:95]
	v_mfma_f32_16x16x32_bf16 v[84:87], v[160:163], v[184:187], v[84:87]
	v_mfma_f32_16x16x32_bf16 v[76:79], v[152:155], v[192:195], v[76:79]
	v_mfma_f32_16x16x32_bf16 v[68:71], v[160:163], v[192:195], v[68:71]
	v_mfma_f32_16x16x32_bf16 v[116:119], v[156:159], v[172:175], v[116:119]
	v_mfma_f32_16x16x32_bf16 v[112:115], v[164:167], v[172:175], v[112:115]
	v_mfma_f32_16x16x32_bf16 v[108:111], v[156:159], v[180:183], v[108:111]
	v_mfma_f32_16x16x32_bf16 v[100:103], v[164:167], v[180:183], v[100:103]
	v_mfma_f32_16x16x32_bf16 v[92:95], v[156:159], v[188:191], v[92:95]
	v_mfma_f32_16x16x32_bf16 v[84:87], v[164:167], v[188:191], v[84:87]
	v_mfma_f32_16x16x32_bf16 v[76:79], v[156:159], v[198:201], v[76:79]
	v_mfma_f32_16x16x32_bf16 v[68:71], v[164:167], v[198:201], v[68:71]
	s_barrier
	s_add_i32 s50, s38, s22
	v_lshl_add_u64 v[218:219], s[26:27], 0, v[130:131]
	s_mov_b32 m0, s50
	ds_read_b128 v[202:205], v149
	ds_read_b128 v[206:209], v149 offset:1024
	ds_read_b128 v[210:213], v149 offset:2048
	ds_read_b128 v[214:217], v149 offset:3072
	global_load_lds_dwordx4 v[218:219], off
	v_lshl_add_u64 v[220:221], s[26:27], 0, v[134:135]
	s_add_i32 m0, s50, 0x2000
	s_nop 0
	global_load_lds_dwordx4 v[220:221], off
	s_barrier
	s_waitcnt lgkmcnt(0)
	s_waitcnt lgkmcnt(0)
	v_mfma_f32_16x16x32_bf16 v[124:127], v[202:205], v[168:171], v[124:127]
	v_mfma_f32_16x16x32_bf16 v[120:123], v[210:213], v[168:171], v[120:123]
	v_mfma_f32_16x16x32_bf16 v[104:107], v[202:205], v[176:179], v[104:107]
	v_mfma_f32_16x16x32_bf16 v[96:99], v[210:213], v[176:179], v[96:99]
	v_mfma_f32_16x16x32_bf16 v[88:91], v[202:205], v[184:187], v[88:91]
	v_mfma_f32_16x16x32_bf16 v[80:83], v[210:213], v[184:187], v[80:83]
	v_mfma_f32_16x16x32_bf16 v[72:75], v[202:205], v[192:195], v[72:75]
	v_mfma_f32_16x16x32_bf16 v[64:67], v[210:213], v[192:195], v[64:67]
	v_mfma_f32_16x16x32_bf16 v[124:127], v[206:209], v[172:175], v[124:127]
	v_mfma_f32_16x16x32_bf16 v[120:123], v[214:217], v[172:175], v[120:123]
	v_mfma_f32_16x16x32_bf16 v[104:107], v[206:209], v[180:183], v[104:107]
	v_mfma_f32_16x16x32_bf16 v[96:99], v[214:217], v[180:183], v[96:99]
	v_mfma_f32_16x16x32_bf16 v[88:91], v[206:209], v[188:191], v[88:91]
	v_mfma_f32_16x16x32_bf16 v[80:83], v[214:217], v[188:191], v[80:83]
	v_mfma_f32_16x16x32_bf16 v[72:75], v[206:209], v[198:201], v[72:75]
	v_mfma_f32_16x16x32_bf16 v[64:67], v[214:217], v[198:201], v[64:67]
	s_mov_b32 m0, s19
	v_lshl_add_u64 v[222:223], s[36:37], 0, v[128:129]
	s_barrier
	ds_read_b128 v[168:171], v148 offset:16384
	ds_read_b128 v[172:175], v148 offset:17408
	ds_read_b128 v[176:179], v148 offset:18432
	ds_read_b128 v[180:183], v148 offset:19456
	ds_read_b128 v[184:187], v148 offset:20480
	ds_read_b128 v[188:191], v148 offset:21504
	ds_read_b128 v[192:195], v148 offset:22528
	ds_read_b128 v[198:201], v148 offset:23552
	global_load_lds_dwordx4 v[222:223], off
	v_lshl_add_u64 v[224:225], s[36:37], 0, v[132:133]
	s_mov_b32 m0, s23
	s_nop 0
	global_load_lds_dwordx4 v[224:225], off
	s_barrier
	s_waitcnt lgkmcnt(0)
	s_waitcnt lgkmcnt(0)
	v_mfma_f32_16x16x32_bf16 v[60:63], v[152:155], v[168:171], v[60:63]
	v_mfma_f32_16x16x32_bf16 v[52:55], v[160:163], v[168:171], v[52:55]
	v_mfma_f32_16x16x32_bf16 v[44:47], v[152:155], v[176:179], v[44:47]
	v_mfma_f32_16x16x32_bf16 v[36:39], v[160:163], v[176:179], v[36:39]
	v_mfma_f32_16x16x32_bf16 v[28:31], v[152:155], v[184:187], v[28:31]
	v_mfma_f32_16x16x32_bf16 v[20:23], v[160:163], v[184:187], v[20:23]
	v_mfma_f32_16x16x32_bf16 v[12:15], v[152:155], v[192:195], v[12:15]
	v_mfma_f32_16x16x32_bf16 v[4:7], v[160:163], v[192:195], v[4:7]
	v_mfma_f32_16x16x32_bf16 v[60:63], v[156:159], v[172:175], v[60:63]
	v_mfma_f32_16x16x32_bf16 v[52:55], v[164:167], v[172:175], v[52:55]
	v_mfma_f32_16x16x32_bf16 v[44:47], v[156:159], v[180:183], v[44:47]
	v_mfma_f32_16x16x32_bf16 v[36:39], v[164:167], v[180:183], v[36:39]
	v_mfma_f32_16x16x32_bf16 v[28:31], v[156:159], v[188:191], v[28:31]
	v_mfma_f32_16x16x32_bf16 v[20:23], v[164:167], v[188:191], v[20:23]
	v_mfma_f32_16x16x32_bf16 v[12:15], v[156:159], v[198:201], v[12:15]
	v_mfma_f32_16x16x32_bf16 v[4:7], v[164:167], v[198:201], v[4:7]
	s_barrier
; #define PG8_STAGE(bufoff, gbase, voff) do { _Pragma("unroll") for (int _i = 0; _i < 2; ++_i) \
;         __builtin_amdgcn_global_load_lds((const unsigned*)((const char*)(gbase) + (voff)[_i]), (LAS unsigned*)(lds + (bufoff) + ldsw + _i * 8192), 16, 0, 0); } while (0)
; #define PG8_LDA(dst, b, h) do { _Pragma("unroll") for (int m = 0; m < 4; ++m) _Pragma("unroll") for (int k = 0; k < 2; ++k) dst[m][k] = *(const LAS bf16x8*)(lds + PG8_SA(b, h) + aoff + m * 2048 + k * 1024); } while (0)
; #define PG8_LDB(dst, b, h) do { _Pragma("unroll") for (int n = 0; n < 2; ++n) _Pragma("unroll") for (int k = 0; k < 2; ++k) dst[n][k] = *(const LAS bf16x8*)(lds + PG8_SB(b, h) + boff + n * 2048 + k * 1024); } while (0)
; #define PG8_MMA(ai, bj, At, Bt) do { __builtin_amdgcn_s_setprio(1); _Pragma("unroll") for (int m = 0; m < 4; ++m) _Pragma("unroll") for (int n = 0; n < 2; ++n) _Pragma("unroll") for (int k = 0; k < 2; ++k) \
;         acc[ai][bj][m][n] = __builtin_amdgcn_mfma_f32_16x16x32_bf16(Bt[n][k], At[m][k], acc[ai][bj][m][n], 0, 0, 0); __builtin_amdgcn_s_setprio(0); } while (0)
; #define PG8_WAIT_V(n) asm volatile("s_waitcnt vmcnt(" #n ")" ::: "memory")
; #define PG8_WAIT_L(n) asm volatile("s_waitcnt lgkmcnt(" #n ")" ::: "memory")
; #define PG8_BAR __builtin_amdgcn_s_barrier()
; #define PG8_SCHED __builtin_amdgcn_sched_barrier(0)
; template <class Epi, class Sched>
; __device__ __forceinline__ void gemm_phase(LAS unsigned char* lds, const Gemm g, const Sched& S, const Epi& E) {
;     ...
;             PG8_STAGE(PG8_SB(0, 1), b2 + hstepB, voffB);
;             PG8_WAIT_V(6); PG8_BAR; PG8_MMA(1, 1, At, B1); PG8_BAR;
;             PG8_LDB(B0, 1, 0); PG8_SCHED; PG8_LDA(At, 1, 0); PG8_STAGE(PG8_SA(0, 1), a2 + hstepA, voffA);
;             PG8_WAIT_L(8); PG8_BAR; PG8_WAIT_L(0); PG8_MMA(0, 0, At, B0); PG8_BAR; PG8_SCHED;
;             PG8_LDB(B1, 1, 1); PG8_STAGE(PG8_SB(1, 0), b3, voffB);
;             PG8_BAR; PG8_WAIT_L(0); PG8_MMA(0, 1, At, B1); PG8_BAR;
;             PG8_LDA(At, 1, 1); PG8_STAGE(PG8_SA(1, 0), a3, voffA);
;             PG8_BAR; PG8_WAIT_L(0); PG8_MMA(1, 0, At, B0); PG8_BAR; PG8_SCHED;
;             PG8_STAGE(PG8_SB(1, 1), b3 + hstepB, voffB);
;             PG8_WAIT_V(6); PG8_BAR; PG8_MMA(1, 1, At, B1); PG8_BAR;
	s_add_u32 s50, s26, 0x80000
	s_addc_u32 s51, s27, 0
	s_add_i32 s52, s39, s22
	v_lshl_add_u64 v[152:153], s[50:51], 0, v[130:131]
	s_mov_b32 m0, s52
	s_nop 0
	global_load_lds_dwordx4 v[152:153], off
	v_lshl_add_u64 v[152:153], s[50:51], 0, v[134:135]
	s_add_i32 m0, s52, 0x2000
	s_nop 0
	global_load_lds_dwordx4 v[152:153], off
	s_waitcnt vmcnt(6)
	s_barrier
	v_mfma_f32_16x16x32_bf16 v[56:59], v[202:205], v[168:171], v[56:59]
	v_mfma_f32_16x16x32_bf16 v[48:51], v[210:213], v[168:171], v[48:51]
	v_mfma_f32_16x16x32_bf16 v[40:43], v[202:205], v[176:179], v[40:43]
	v_mfma_f32_16x16x32_bf16 v[32:35], v[210:213], v[176:179], v[32:35]
	v_mfma_f32_16x16x32_bf16 v[24:27], v[202:205], v[184:187], v[24:27]
	v_mfma_f32_16x16x32_bf16 v[16:19], v[210:213], v[184:187], v[16:19]
	v_mfma_f32_16x16x32_bf16 v[8:11], v[202:205], v[192:195], v[8:11]
	v_mfma_f32_16x16x32_bf16 v[0:3], v[210:213], v[192:195], v[0:3]
	v_mfma_f32_16x16x32_bf16 v[56:59], v[206:209], v[172:175], v[56:59]
	v_mfma_f32_16x16x32_bf16 v[48:51], v[214:217], v[172:175], v[48:51]
	v_mfma_f32_16x16x32_bf16 v[40:43], v[206:209], v[180:183], v[40:43]
	v_mfma_f32_16x16x32_bf16 v[32:35], v[214:217], v[180:183], v[32:35]
	v_mfma_f32_16x16x32_bf16 v[24:27], v[206:209], v[188:191], v[24:27]
	v_mfma_f32_16x16x32_bf16 v[16:19], v[214:217], v[188:191], v[16:19]
	v_mfma_f32_16x16x32_bf16 v[8:11], v[206:209], v[198:201], v[8:11]
	v_mfma_f32_16x16x32_bf16 v[0:3], v[214:217], v[198:201], v[0:3]
	s_add_i32 s50, 0, 0x18000
	v_add_u32_e32 v151, s50, v145
	s_barrier
	ds_read_b128 v[152:155], v151
	ds_read_b128 v[156:159], v151 offset:1024
	ds_read_b128 v[160:163], v151 offset:2048
	ds_read_b128 v[164:167], v151 offset:3072
	s_add_u32 s36, s36, 0x80000
	s_addc_u32 s37, s37, 0
	s_mov_b32 m0, s29
	v_lshl_add_u64 v[202:203], s[36:37], 0, v[128:129]
	ds_read_b128 v[168:171], v148 offset:32768
	ds_read_b128 v[172:175], v148 offset:33792
	ds_read_b128 v[176:179], v148 offset:34816
	ds_read_b128 v[180:183], v148 offset:35840
	ds_read_b128 v[184:187], v148 offset:36864
	ds_read_b128 v[188:191], v148 offset:37888
	ds_read_b128 v[192:195], v148 offset:38912
	ds_read_b128 v[198:201], v148 offset:39936
	global_load_lds_dwordx4 v[202:203], off
	v_lshl_add_u64 v[202:203], s[36:37], 0, v[132:133]
	s_mov_b32 m0, s30
	s_nop 0
	global_load_lds_dwordx4 v[202:203], off
	s_waitcnt lgkmcnt(8)
	s_barrier
	s_waitcnt lgkmcnt(0)
	s_waitcnt lgkmcnt(0)
	v_mfma_f32_16x16x32_bf16 v[116:119], v[152:155], v[168:171], v[116:119]
	v_mfma_f32_16x16x32_bf16 v[112:115], v[160:163], v[168:171], v[112:115]
	v_mfma_f32_16x16x32_bf16 v[108:111], v[152:155], v[176:179], v[108:111]
	v_mfma_f32_16x16x32_bf16 v[100:103], v[160:163], v[176:179], v[100:103]
	v_mfma_f32_16x16x32_bf16 v[92:95], v[152:155], v[184:187], v[92:95]
	v_mfma_f32_16x16x32_bf16 v[84:87], v[160:163], v[184:187], v[84:87]
	v_mfma_f32_16x16x32_bf16 v[76:79], v[152:155], v[192:195], v[76:79]
	v_mfma_f32_16x16x32_bf16 v[68:71], v[160:163], v[192:195], v[68:71]
	v_mfma_f32_16x16x32_bf16 v[116:119], v[156:159], v[172:175], v[116:119]
	v_mfma_f32_16x16x32_bf16 v[112:115], v[164:167], v[172:175], v[112:115]
	v_mfma_f32_16x16x32_bf16 v[108:111], v[156:159], v[180:183], v[108:111]
	v_mfma_f32_16x16x32_bf16 v[100:103], v[164:167], v[180:183], v[100:103]
	v_mfma_f32_16x16x32_bf16 v[92:95], v[156:159], v[188:191], v[92:95]
	v_mfma_f32_16x16x32_bf16 v[84:87], v[164:167], v[188:191], v[84:87]
	v_mfma_f32_16x16x32_bf16 v[76:79], v[156:159], v[198:201], v[76:79]
	v_mfma_f32_16x16x32_bf16 v[68:71], v[164:167], v[198:201], v[68:71]
	s_barrier
	s_add_i32 s36, 0, 0x1c000
	s_add_i32 s37, s50, s22
	v_add_u32_e32 v151, s36, v145
	v_lshl_add_u64 v[218:219], v[218:219], 0, s[6:7]
	s_mov_b32 m0, s37
	ds_read_b128 v[202:205], v151
	ds_read_b128 v[206:209], v151 offset:1024
	ds_read_b128 v[210:213], v151 offset:2048
	ds_read_b128 v[214:217], v151 offset:3072
	global_load_lds_dwordx4 v[218:219], off
	v_lshl_add_u64 v[218:219], v[220:221], 0, s[6:7]
	s_add_i32 m0, s37, 0x2000
	s_nop 0
	global_load_lds_dwordx4 v[218:219], off
	s_barrier
	s_waitcnt lgkmcnt(0)
	s_waitcnt lgkmcnt(0)
	v_mfma_f32_16x16x32_bf16 v[124:127], v[202:205], v[168:171], v[124:127]
	v_mfma_f32_16x16x32_bf16 v[120:123], v[210:213], v[168:171], v[120:123]
	v_mfma_f32_16x16x32_bf16 v[104:107], v[202:205], v[176:179], v[104:107]
	v_mfma_f32_16x16x32_bf16 v[96:99], v[210:213], v[176:179], v[96:99]
	v_mfma_f32_16x16x32_bf16 v[88:91], v[202:205], v[184:187], v[88:91]
	v_mfma_f32_16x16x32_bf16 v[80:83], v[210:213], v[184:187], v[80:83]
	v_mfma_f32_16x16x32_bf16 v[72:75], v[202:205], v[192:195], v[72:75]
	v_mfma_f32_16x16x32_bf16 v[64:67], v[210:213], v[192:195], v[64:67]
	v_mfma_f32_16x16x32_bf16 v[124:127], v[206:209], v[172:175], v[124:127]
	v_mfma_f32_16x16x32_bf16 v[120:123], v[214:217], v[172:175], v[120:123]
	v_mfma_f32_16x16x32_bf16 v[104:107], v[206:209], v[180:183], v[104:107]
	v_mfma_f32_16x16x32_bf16 v[96:99], v[214:217], v[180:183], v[96:99]
	v_mfma_f32_16x16x32_bf16 v[88:91], v[206:209], v[188:191], v[88:91]
	v_mfma_f32_16x16x32_bf16 v[80:83], v[214:217], v[188:191], v[80:83]
	v_mfma_f32_16x16x32_bf16 v[72:75], v[206:209], v[198:201], v[72:75]
	v_mfma_f32_16x16x32_bf16 v[64:67], v[214:217], v[198:201], v[64:67]
	s_mov_b32 m0, s33
	v_lshl_add_u64 v[218:219], v[222:223], 0, s[6:7]
	s_barrier
	ds_read_b128 v[168:171], v148 offset:49152
	ds_read_b128 v[172:175], v148 offset:50176
	ds_read_b128 v[176:179], v148 offset:51200
	ds_read_b128 v[180:183], v148 offset:52224
	ds_read_b128 v[184:187], v148 offset:53248
	ds_read_b128 v[188:191], v148 offset:54272
	ds_read_b128 v[192:195], v148 offset:55296
	ds_read_b128 v[198:201], v148 offset:56320
	global_load_lds_dwordx4 v[218:219], off
	v_lshl_add_u64 v[218:219], v[224:225], 0, s[6:7]
	s_mov_b32 m0, s34
	s_nop 0
	global_load_lds_dwordx4 v[218:219], off
	s_barrier
; __device__ __forceinline__ unsigned pk_bf16(float lo, float hi) { unsigned r; asm volatile("v_cvt_pk_bf16_f32 %0, %1, %2" : "=v"(r) : "v"(lo), "v"(hi)); return r; }
; __device__ __forceinline__ float sigmoidf_(float x) { return __builtin_amdgcn_rcpf(1.0f + __expf(-x)); }
;     __device__ __forceinline__ void operator()(const f32x4 (&acc)[2][2][4][2], const Unit& u, int wr, int wc, int fr, int fq) const {
;     ...
;             for (int m = 0; m < 4; ++m) rs[ai][m] = rowsq[row0 + ai * 128 + m * 16];
; #pragma unroll
;         for (int ai = 0; ai < 2; ++ai)
; #pragma unroll
;             for (int m = 0; m < 4; ++m) {
;                 const int row = row0 + ai * 128 + m * 16;
;                 const float rstd = rsqrtf(rs[ai][m] * (1.0f / D) + RMS_EPS);
;                 f32x4 o[2];
; #pragma unroll
;                 for (int n = 0; n < 2; ++n)
; #pragma unroll
;                     for (int j = 0; j < 4; ++j) { const float gt = acc[ai][0][m][n][j] * rstd, up = acc[ai][1][m][n][j] * rstd; o[n][j] = gt * sigmoidf_(gt) * up; }
;                 u32x4 w; w.x = pk_bf16(o[0][0], o[0][1]); w.y = pk_bf16(o[0][2], o[0][3]); w.z = pk_bf16(o[1][0], o[1][1]); w.w = pk_bf16(o[1][2], o[1][3]);
;                 *(u32x4*)(U + (size_t)row * DFF + col0) = w;
	s_waitcnt lgkmcnt(0)
	s_waitcnt lgkmcnt(0)
	v_mfma_f32_16x16x32_bf16 v[60:63], v[152:155], v[168:171], v[60:63]
	v_mfma_f32_16x16x32_bf16 v[52:55], v[160:163], v[168:171], v[52:55]
	v_mfma_f32_16x16x32_bf16 v[44:47], v[152:155], v[176:179], v[44:47]
	v_mfma_f32_16x16x32_bf16 v[36:39], v[160:163], v[176:179], v[36:39]
	v_mfma_f32_16x16x32_bf16 v[28:31], v[152:155], v[184:187], v[28:31]
	v_mfma_f32_16x16x32_bf16 v[20:23], v[160:163], v[184:187], v[20:23]
	v_mfma_f32_16x16x32_bf16 v[12:15], v[152:155], v[192:195], v[12:15]
	v_mfma_f32_16x16x32_bf16 v[4:7], v[160:163], v[192:195], v[4:7]
	v_mfma_f32_16x16x32_bf16 v[60:63], v[156:159], v[172:175], v[60:63]
	v_mfma_f32_16x16x32_bf16 v[52:55], v[164:167], v[172:175], v[52:55]
	v_mfma_f32_16x16x32_bf16 v[44:47], v[156:159], v[180:183], v[44:47]
	v_mfma_f32_16x16x32_bf16 v[36:39], v[164:167], v[180:183], v[36:39]
	v_mfma_f32_16x16x32_bf16 v[28:31], v[156:159], v[188:191], v[28:31]
	v_mfma_f32_16x16x32_bf16 v[20:23], v[164:167], v[188:191], v[20:23]
	v_mfma_f32_16x16x32_bf16 v[12:15], v[156:159], v[198:201], v[12:15]
	v_mfma_f32_16x16x32_bf16 v[4:7], v[164:167], v[198:201], v[4:7]
	s_barrier
	s_add_u32 s26, s26, 0x80080
	s_addc_u32 s27, s27, 0
	s_add_i32 s36, s36, s22
	v_lshl_add_u64 v[152:153], s[26:27], 0, v[130:131]
	s_mov_b32 m0, s36
	s_nop 0
	global_load_lds_dwordx4 v[152:153], off
	v_lshl_add_u64 v[152:153], s[26:27], 0, v[134:135]
	s_add_i32 m0, s36, 0x2000
	s_nop 0
	global_load_lds_dwordx4 v[152:153], off
	s_waitcnt vmcnt(6)
	s_barrier
	v_mfma_f32_16x16x32_bf16 v[56:59], v[202:205], v[168:171], v[56:59]
	v_mfma_f32_16x16x32_bf16 v[48:51], v[210:213], v[168:171], v[48:51]
	v_mfma_f32_16x16x32_bf16 v[40:43], v[202:205], v[176:179], v[40:43]
	v_mfma_f32_16x16x32_bf16 v[32:35], v[210:213], v[176:179], v[32:35]
	v_mfma_f32_16x16x32_bf16 v[24:27], v[202:205], v[184:187], v[24:27]
	v_mfma_f32_16x16x32_bf16 v[16:19], v[210:213], v[184:187], v[16:19]
	v_mfma_f32_16x16x32_bf16 v[8:11], v[202:205], v[192:195], v[8:11]
	v_mfma_f32_16x16x32_bf16 v[0:3], v[210:213], v[192:195], v[0:3]
	v_mfma_f32_16x16x32_bf16 v[56:59], v[206:209], v[172:175], v[56:59]
	v_mfma_f32_16x16x32_bf16 v[48:51], v[214:217], v[172:175], v[48:51]
	v_mfma_f32_16x16x32_bf16 v[40:43], v[206:209], v[180:183], v[40:43]
	v_mfma_f32_16x16x32_bf16 v[32:35], v[214:217], v[180:183], v[32:35]
	v_mfma_f32_16x16x32_bf16 v[24:27], v[206:209], v[188:191], v[24:27]
	v_mfma_f32_16x16x32_bf16 v[16:19], v[214:217], v[188:191], v[16:19]
	v_mfma_f32_16x16x32_bf16 v[8:11], v[206:209], v[198:201], v[8:11]
	v_mfma_f32_16x16x32_bf16 v[0:3], v[214:217], v[198:201], v[0:3]
	s_add_i32 s45, s45, 2
	s_add_u32 s24, s24, 0x100
	s_addc_u32 s25, s25, 0
	s_add_u32 s43, s43, 0x100
	s_addc_u32 s44, s44, 0
	s_cmp_gt_u32 s45, 29
	s_barrier
	s_cbranch_scc0 .LBB0_1209
	s_setprio 0
	v_lshl_add_u32 v154, s18, 8, v144
	v_ashrrev_i32_e32 v155, 31, v154
	v_lshl_add_u64 v[156:157], v[154:155], 2, s[96:97]
	v_mov_b32_e32 v155, v228
	v_or_b32_e32 v168, 16, v154
	v_ashrrev_i32_e32 v169, 31, v168
	v_lshl_add_u64 v[170:171], v[168:169], 2, s[96:97]
	v_mov_b32_e32 v169, v229
	v_mov_b32_e32 v166, v122
	v_or_b32_e32 v122, 48, v154
	v_mov_b32_e32 v160, v124
	v_mov_b32_e32 v167, v114
	v_mov_b32_e32 v114, v123
	v_or_b32_e32 v124, 32, v154
	v_ashrrev_i32_e32 v123, 31, v122
	v_mov_b32_e32 v161, v116
	v_mov_b32_e32 v116, v125
	v_ashrrev_i32_e32 v125, 31, v124
	v_lshl_add_u64 v[172:173], v[122:123], 2, s[96:97]
	v_lshl_add_u64 v[170:171], v[124:125], 2, s[96:97]
	v_mov_b32_e32 v162, v126
	v_mov_b32_e32 v174, v232
	v_mov_b32_e32 v153, v233
	v_mov_b32_e32 v151, v197
	s_nop 0
	v_mov_b32_e32 v170, v230
	s_nop 0
	v_mov_b32_e32 v171, v231
	v_mov_b32_e32 v126, v226
	v_mov_b32_e32 v165, v112
	v_mov_b32_e32 v112, v121
	v_mov_b32_e32 v163, v118
	v_mov_b32_e32 v118, v127
	v_mov_b32_e32 v164, v120
	v_mov_b64_e32 v[120:121], s[48:49]
	v_add_u32_e32 v152, 0x80, v154
	v_add_u32_e32 v127, 0x90, v154
	v_lshl_or_b32 v158, s42, 7, v146
	v_ashrrev_i32_e32 v159, 31, v158
	s_mov_b32 s42, s8
	s_mov_b32 s18, s10
	s_mov_b64 s[26:27], s[16:17]
	s_mov_b64 s[24:25], s[12:13]
	s_waitcnt vmcnt(0)
	v_fmamk_f32 v123, v155, 0x3a000000, v150
	v_mul_f32_e32 v125, 0x4b800000, v123
	v_cmp_gt_f32_e32 vcc, s40, v123
	s_nop 1
	v_cndmask_b32_e32 v123, v123, v125, vcc
	v_rsq_f32_e32 v155, v123
	v_add_u32_e32 v125, 0xa0, v154
	v_add_u32_e32 v123, 0xb0, v154
	v_mul_f32_e32 v156, 0x45800000, v155
	v_cndmask_b32_e32 v156, v155, v156, vcc
	v_pk_mul_f32 v[116:117], v[116:117], v[156:157] op_sel_hi:[1,0]
	v_pk_mul_f32 v[112:113], v[112:113], v[156:157] op_sel_hi:[1,0]
	v_pk_mul_f32 v[160:161], v[160:161], v[156:157] op_sel_hi:[1,0]
	v_pk_mul_f32 v[162:163], v[162:163], v[156:157] op_sel_hi:[1,0]
	v_pk_mul_f32 v[118:119], v[118:119], v[156:157] op_sel_hi:[1,0]
	v_pk_mul_f32 v[164:165], v[164:165], v[156:157] op_sel_hi:[1,0]
	v_pk_mul_f32 v[166:167], v[166:167], v[156:157] op_sel_hi:[1,0]
	v_pk_mul_f32 v[114:115], v[114:115], v[156:157] op_sel_hi:[1,0]
	v_mul_f32_e32 v156, 0xbfb8aa3b, v117
	v_mul_f32_e32 v175, 0xbfb8aa3b, v113
	v_mul_f32_e32 v155, 0xbfb8aa3b, v161
	v_mul_f32_e32 v157, 0xbfb8aa3b, v163
	v_mul_f32_e32 v172, 0xbfb8aa3b, v119
	v_mul_f32_e32 v173, 0xbfb8aa3b, v165
	v_mul_f32_e32 v176, 0xbfb8aa3b, v167
	v_mul_f32_e32 v177, 0xbfb8aa3b, v115
	v_exp_f32_e32 v156, v156
	v_exp_f32_e32 v175, v175
	v_exp_f32_e32 v155, v155
	v_exp_f32_e32 v157, v157
	v_exp_f32_e32 v172, v172
	v_exp_f32_e32 v173, v173
	v_exp_f32_e32 v176, v176
	v_exp_f32_e32 v177, v177
	v_add_f32_e32 v156, 1.0, v156
	v_add_f32_e32 v175, 1.0, v175
	v_add_f32_e32 v155, 1.0, v155
	v_add_f32_e32 v157, 1.0, v157
	v_add_f32_e32 v172, 1.0, v172
	v_add_f32_e32 v173, 1.0, v173
; __device__ __forceinline__ unsigned pk_bf16(float lo, float hi) { unsigned r; asm volatile("v_cvt_pk_bf16_f32 %0, %1, %2" : "=v"(r) : "v"(lo), "v"(hi)); return r; }
; __device__ __forceinline__ float sigmoidf_(float x) { return __builtin_amdgcn_rcpf(1.0f + __expf(-x)); }
;     __device__ __forceinline__ void operator()(const f32x4 (&acc)[2][2][4][2], const Unit& u, int wr, int wc, int fr, int fq) const {
;     ...
;         for (int ai = 0; ai < 2; ++ai)
; #pragma unroll
;             for (int m = 0; m < 4; ++m) {
;                 const int row = row0 + ai * 128 + m * 16;
;                 const float rstd = rsqrtf(rs[ai][m] * (1.0f / D) + RMS_EPS);
;                 f32x4 o[2];
; #pragma unroll
;                 for (int n = 0; n < 2; ++n)
; #pragma unroll
;                     for (int j = 0; j < 4; ++j) { const float gt = acc[ai][0][m][n][j] * rstd, up = acc[ai][1][m][n][j] * rstd; o[n][j] = gt * sigmoidf_(gt) * up; }
;                 u32x4 w; w.x = pk_bf16(o[0][0], o[0][1]); w.y = pk_bf16(o[0][2], o[0][3]); w.z = pk_bf16(o[1][0], o[1][1]); w.w = pk_bf16(o[1][2], o[1][3]);
;                 *(u32x4*)(U + (size_t)row * DFF + col0) = w;
	v_add_f32_e32 v176, 1.0, v176
	v_add_f32_e32 v177, 1.0, v177
	v_rcp_f32_e32 v156, v156
	v_rcp_f32_e32 v175, v175
	v_rcp_f32_e32 v155, v155
	v_rcp_f32_e32 v157, v157
	v_rcp_f32_e32 v172, v172
	v_rcp_f32_e32 v173, v173
	v_rcp_f32_e32 v176, v176
	v_rcp_f32_e32 v177, v177
	v_mul_f32_e32 v117, v117, v156
	v_mul_f32_e32 v113, v113, v175
	v_mul_f32_e32 v155, v161, v155
	v_mul_f32_e32 v156, v163, v157
	v_mul_f32_e32 v119, v119, v172
	v_mul_f32_e32 v157, v165, v173
	v_mul_f32_e32 v161, v167, v176
	v_mul_f32_e32 v115, v115, v177
	v_mul_f32_e32 v116, v116, v117
	v_mul_f32_e32 v112, v112, v113
	v_mul_f32_e32 v155, v160, v155
	v_mul_f32_e32 v117, v162, v156
	v_mul_f32_e32 v118, v118, v119
	v_mul_f32_e32 v119, v164, v157
	v_mul_f32_e32 v113, v166, v161
	v_mul_f32_e32 v156, v114, v115
	v_cvt_pk_bf16_f32 v114, v155, v116
	v_cvt_pk_bf16_f32 v115, v117, v118
	v_cvt_pk_bf16_f32 v116, v119, v112
	v_fmamk_f32 v112, v169, 0x3a000000, v150
	v_cvt_pk_bf16_f32 v117, v113, v156
	v_mul_f32_e32 v113, 0x4b800000, v112
	v_cmp_gt_f32_e32 vcc, s40, v112
	v_mad_i64_i32 v[118:119], s[4:5], v154, s41, v[120:121]
	s_nop 0
	v_cndmask_b32_e32 v112, v112, v113, vcc
	v_rsq_f32_e32 v155, v112
	v_mov_b32_e32 v156, v104
	v_mov_b32_e32 v157, v108
	v_mov_b32_e32 v108, v105
	v_mul_f32_e32 v154, 0x45800000, v155
	v_cndmask_b32_e32 v154, v155, v154, vcc
	v_pk_mul_f32 v[156:157], v[156:157], v[154:155] op_sel_hi:[1,0]
	v_lshlrev_b64 v[112:113], 1, v[158:159]
	v_mul_f32_e32 v104, 0xbfb8aa3b, v157
	v_exp_f32_e32 v155, v104
	s_nop 0
	v_pk_mul_f32 v[104:105], v[108:109], v[154:155] op_sel_hi:[1,0]
	s_nop 0
	v_mul_f32_e32 v108, 0xbfb8aa3b, v105
	v_exp_f32_e32 v158, v108
	v_lshl_add_u64 v[108:109], v[118:119], 0, v[112:113]
	v_add_f32_e32 v118, 1.0, v155
	v_rcp_f32_e32 v118, v118
	global_store_dwordx4 v[108:109], v[114:117], off
	v_mov_b32_e32 v109, v110
	v_add_f32_e32 v119, 1.0, v158
	v_mul_f32_e32 v108, v157, v118
	v_mul_f32_e32 v114, v156, v108
	v_mov_b32_e32 v108, v106
	v_pk_mul_f32 v[108:109], v[108:109], v[154:155] op_sel_hi:[1,0]
	v_mov_b32_e32 v110, v107
	v_mul_f32_e32 v106, 0xbfb8aa3b, v109
	v_rcp_f32_e32 v119, v119
	v_exp_f32_e32 v115, v106
	v_pk_mul_f32 v[106:107], v[110:111], v[154:155] op_sel_hi:[1,0]
	v_mul_f32_e32 v105, v105, v119
	v_mul_f32_e32 v110, 0xbfb8aa3b, v107
	v_exp_f32_e32 v110, v110
	v_mul_f32_e32 v111, v104, v105
	v_add_f32_e32 v104, 1.0, v115
	v_rcp_f32_e32 v115, v104
	v_add_f32_e32 v104, 1.0, v110
	v_rcp_f32_e32 v110, v104
	v_mov_b32_e32 v104, v96
	v_mov_b32_e32 v105, v100
	v_pk_mul_f32 v[104:105], v[104:105], v[154:155] op_sel_hi:[1,0]
	v_mul_f32_e32 v100, v109, v115
	v_mul_f32_e32 v96, 0xbfb8aa3b, v105
	v_exp_f32_e32 v96, v96
	v_mul_f32_e32 v108, v108, v100
	v_mov_b32_e32 v100, v97
	v_mul_f32_e32 v107, v107, v110
	v_add_f32_e32 v96, 1.0, v96
	v_rcp_f32_e32 v109, v96
	v_pk_mul_f32 v[96:97], v[100:101], v[154:155] op_sel_hi:[1,0]
	v_mul_f32_e32 v106, v106, v107
	v_mul_f32_e32 v100, 0xbfb8aa3b, v97
	v_exp_f32_e32 v100, v100
	v_mul_f32_e32 v101, v105, v109
	v_mul_f32_e32 v104, v104, v101
	v_mov_b32_e32 v101, v102
	v_add_f32_e32 v100, 1.0, v100
	v_rcp_f32_e32 v105, v100
	v_mov_b32_e32 v100, v98
	v_pk_mul_f32 v[100:101], v[100:101], v[154:155] op_sel_hi:[1,0]
	v_mov_b32_e32 v102, v99
	v_mul_f32_e32 v98, 0xbfb8aa3b, v101
	v_exp_f32_e32 v107, v98
	v_pk_mul_f32 v[98:99], v[102:103], v[154:155] op_sel_hi:[1,0]
	v_mul_f32_e32 v97, v97, v105
	v_mul_f32_e32 v102, 0xbfb8aa3b, v99
	v_exp_f32_e32 v102, v102
	v_add_f32_e32 v103, 1.0, v107
	v_rcp_f32_e32 v103, v103
	v_mul_f32_e32 v105, v96, v97
	v_add_f32_e32 v102, 1.0, v102
	v_rcp_f32_e32 v102, v102
	v_mul_f32_e32 v96, v101, v103
	v_fmamk_f32 v101, v170, 0x3a000000, v150
	v_mul_f32_e32 v100, v100, v96
	v_mul_f32_e32 v96, v99, v102
	v_mul_f32_e32 v102, 0x4b800000, v101
	v_cmp_gt_f32_e32 vcc, s40, v101
	v_mul_f32_e32 v99, v98, v96
	v_cvt_pk_bf16_f32 v96, v114, v111
	v_cvt_pk_bf16_f32 v97, v108, v106
	v_cvt_pk_bf16_f32 v98, v104, v105
	v_mov_b32_e32 v104, v88
	v_cndmask_b32_e32 v101, v101, v102, vcc
	v_rsq_f32_e32 v102, v101
	v_mov_b32_e32 v105, v92
	v_mov_b32_e32 v92, v89
	v_cvt_pk_bf16_f32 v99, v100, v99
	v_mul_f32_e32 v103, 0x45800000, v102
	v_cndmask_b32_e32 v102, v102, v103, vcc
	v_pk_mul_f32 v[104:105], v[104:105], v[102:103] op_sel_hi:[1,0]
	v_mad_i64_i32 v[100:101], s[4:5], v168, s41, v[120:121]
	v_mul_f32_e32 v88, 0xbfb8aa3b, v105
	v_exp_f32_e32 v103, v88
	s_nop 0
	v_pk_mul_f32 v[88:89], v[92:93], v[102:103] op_sel_hi:[1,0]
	s_nop 0
	v_mul_f32_e32 v92, 0xbfb8aa3b, v89
	v_exp_f32_e32 v106, v92
	v_lshl_add_u64 v[92:93], v[100:101], 0, v[112:113]
	v_add_f32_e32 v100, 1.0, v103
	v_rcp_f32_e32 v100, v100
	global_store_dwordx4 v[92:93], v[96:99], off
	v_mov_b32_e32 v93, v94
	v_add_f32_e32 v101, 1.0, v106
	v_mul_f32_e32 v92, v105, v100
	v_mul_f32_e32 v96, v104, v92
	v_mov_b32_e32 v92, v90
	v_pk_mul_f32 v[92:93], v[92:93], v[102:103] op_sel_hi:[1,0]
	v_mov_b32_e32 v94, v91
	v_mul_f32_e32 v90, 0xbfb8aa3b, v93
	v_rcp_f32_e32 v101, v101
	v_exp_f32_e32 v97, v90
	v_pk_mul_f32 v[90:91], v[94:95], v[102:103] op_sel_hi:[1,0]
	v_mul_f32_e32 v89, v89, v101
	v_mul_f32_e32 v94, 0xbfb8aa3b, v91
	v_exp_f32_e32 v94, v94
	v_mul_f32_e32 v95, v88, v89
	v_add_f32_e32 v88, 1.0, v97
	v_rcp_f32_e32 v97, v88
	v_add_f32_e32 v88, 1.0, v94
	v_rcp_f32_e32 v94, v88
	v_mov_b32_e32 v88, v80
	v_mov_b32_e32 v89, v84
	v_pk_mul_f32 v[88:89], v[88:89], v[102:103] op_sel_hi:[1,0]
	v_mul_f32_e32 v84, v93, v97
	v_mul_f32_e32 v80, 0xbfb8aa3b, v89
	v_exp_f32_e32 v80, v80
	v_mul_f32_e32 v92, v92, v84
	v_mov_b32_e32 v84, v81
	v_mul_f32_e32 v91, v91, v94
	v_add_f32_e32 v80, 1.0, v80
	v_rcp_f32_e32 v93, v80
	v_pk_mul_f32 v[80:81], v[84:85], v[102:103] op_sel_hi:[1,0]
; __device__ __forceinline__ unsigned pk_bf16(float lo, float hi) { unsigned r; asm volatile("v_cvt_pk_bf16_f32 %0, %1, %2" : "=v"(r) : "v"(lo), "v"(hi)); return r; }
; __device__ __forceinline__ float sigmoidf_(float x) { return __builtin_amdgcn_rcpf(1.0f + __expf(-x)); }
;     __device__ __forceinline__ void operator()(const f32x4 (&acc)[2][2][4][2], const Unit& u, int wr, int wc, int fr, int fq) const {
;     ...
;         for (int ai = 0; ai < 2; ++ai)
; #pragma unroll
;             for (int m = 0; m < 4; ++m) {
;                 const int row = row0 + ai * 128 + m * 16;
;                 const float rstd = rsqrtf(rs[ai][m] * (1.0f / D) + RMS_EPS);
;                 f32x4 o[2];
; #pragma unroll
;                 for (int n = 0; n < 2; ++n)
; #pragma unroll
;                     for (int j = 0; j < 4; ++j) { const float gt = acc[ai][0][m][n][j] * rstd, up = acc[ai][1][m][n][j] * rstd; o[n][j] = gt * sigmoidf_(gt) * up; }
;                 u32x4 w; w.x = pk_bf16(o[0][0], o[0][1]); w.y = pk_bf16(o[0][2], o[0][3]); w.z = pk_bf16(o[1][0], o[1][1]); w.w = pk_bf16(o[1][2], o[1][3]);
;                 *(u32x4*)(U + (size_t)row * DFF + col0) = w;
	v_mul_f32_e32 v90, v90, v91
	v_mul_f32_e32 v84, 0xbfb8aa3b, v81
	v_exp_f32_e32 v84, v84
	v_mul_f32_e32 v85, v89, v93
	v_mul_f32_e32 v88, v88, v85
	v_mov_b32_e32 v85, v86
	v_add_f32_e32 v84, 1.0, v84
	v_rcp_f32_e32 v89, v84
	v_mov_b32_e32 v84, v82
	v_pk_mul_f32 v[84:85], v[84:85], v[102:103] op_sel_hi:[1,0]
	v_mov_b32_e32 v86, v83
	v_mul_f32_e32 v82, 0xbfb8aa3b, v85
	v_exp_f32_e32 v91, v82
	v_pk_mul_f32 v[82:83], v[86:87], v[102:103] op_sel_hi:[1,0]
	v_mul_f32_e32 v81, v81, v89
	v_mul_f32_e32 v86, 0xbfb8aa3b, v83
	v_exp_f32_e32 v86, v86
	v_add_f32_e32 v87, 1.0, v91
	v_rcp_f32_e32 v87, v87
	v_mul_f32_e32 v89, v80, v81
	v_add_f32_e32 v86, 1.0, v86
	v_rcp_f32_e32 v86, v86
	v_mul_f32_e32 v80, v85, v87
	v_fmamk_f32 v85, v171, 0x3a000000, v150
	v_mul_f32_e32 v84, v84, v80
	v_mul_f32_e32 v80, v83, v86
	v_mul_f32_e32 v86, 0x4b800000, v85
	v_cmp_gt_f32_e32 vcc, s40, v85
	v_mul_f32_e32 v83, v82, v80
	v_cvt_pk_bf16_f32 v80, v96, v95
	v_cvt_pk_bf16_f32 v81, v92, v90
	v_cvt_pk_bf16_f32 v82, v88, v89
	v_mov_b32_e32 v88, v72
	v_cndmask_b32_e32 v85, v85, v86, vcc
	v_rsq_f32_e32 v86, v85
	v_mov_b32_e32 v89, v76
	v_mov_b32_e32 v76, v73
	v_cvt_pk_bf16_f32 v83, v84, v83
	v_mul_f32_e32 v87, 0x45800000, v86
	v_cndmask_b32_e32 v86, v86, v87, vcc
	v_pk_mul_f32 v[88:89], v[88:89], v[86:87] op_sel_hi:[1,0]
	v_mad_i64_i32 v[84:85], s[4:5], v124, s41, v[120:121]
	v_mul_f32_e32 v72, 0xbfb8aa3b, v89
	v_exp_f32_e32 v87, v72
	s_nop 0
	v_pk_mul_f32 v[72:73], v[76:77], v[86:87] op_sel_hi:[1,0]
	s_nop 0
	v_mul_f32_e32 v76, 0xbfb8aa3b, v73
	v_exp_f32_e32 v90, v76
	v_lshl_add_u64 v[76:77], v[84:85], 0, v[112:113]
	v_add_f32_e32 v84, 1.0, v87
	v_rcp_f32_e32 v84, v84
	global_store_dwordx4 v[76:77], v[80:83], off
	v_mov_b32_e32 v77, v78
	v_add_f32_e32 v85, 1.0, v90
	v_mul_f32_e32 v76, v89, v84
	v_mul_f32_e32 v80, v88, v76
	v_mov_b32_e32 v76, v74
	v_pk_mul_f32 v[76:77], v[76:77], v[86:87] op_sel_hi:[1,0]
	v_mov_b32_e32 v78, v75
	v_mul_f32_e32 v74, 0xbfb8aa3b, v77
	v_rcp_f32_e32 v85, v85
	v_exp_f32_e32 v81, v74
	v_pk_mul_f32 v[74:75], v[78:79], v[86:87] op_sel_hi:[1,0]
	v_mul_f32_e32 v73, v73, v85
	v_mul_f32_e32 v78, 0xbfb8aa3b, v75
	v_exp_f32_e32 v78, v78
	v_mul_f32_e32 v79, v72, v73
	v_add_f32_e32 v72, 1.0, v81
	v_rcp_f32_e32 v81, v72
	v_add_f32_e32 v72, 1.0, v78
	v_rcp_f32_e32 v78, v72
	v_mov_b32_e32 v72, v64
	v_mov_b32_e32 v73, v68
	v_pk_mul_f32 v[72:73], v[72:73], v[86:87] op_sel_hi:[1,0]
	v_mul_f32_e32 v68, v77, v81
	v_mul_f32_e32 v64, 0xbfb8aa3b, v73
	v_exp_f32_e32 v64, v64
	v_mul_f32_e32 v76, v76, v68
	v_mov_b32_e32 v68, v65
	v_mul_f32_e32 v75, v75, v78
	v_add_f32_e32 v64, 1.0, v64
	v_rcp_f32_e32 v77, v64
	v_pk_mul_f32 v[64:65], v[68:69], v[86:87] op_sel_hi:[1,0]
	v_mul_f32_e32 v74, v74, v75
	v_mul_f32_e32 v68, 0xbfb8aa3b, v65
	v_exp_f32_e32 v68, v68
	v_mul_f32_e32 v69, v73, v77
	v_mul_f32_e32 v72, v72, v69
	v_mov_b32_e32 v69, v70
	v_add_f32_e32 v68, 1.0, v68
	v_rcp_f32_e32 v73, v68
	v_mov_b32_e32 v68, v66
	v_pk_mul_f32 v[68:69], v[68:69], v[86:87] op_sel_hi:[1,0]
	v_mov_b32_e32 v70, v67
	v_mul_f32_e32 v66, 0xbfb8aa3b, v69
	v_exp_f32_e32 v75, v66
	v_pk_mul_f32 v[66:67], v[70:71], v[86:87] op_sel_hi:[1,0]
	v_mul_f32_e32 v65, v65, v73
	v_mul_f32_e32 v70, 0xbfb8aa3b, v67
	v_exp_f32_e32 v70, v70
	v_add_f32_e32 v71, 1.0, v75
	v_rcp_f32_e32 v71, v71
	v_mul_f32_e32 v73, v64, v65
	v_add_f32_e32 v70, 1.0, v70
	v_rcp_f32_e32 v70, v70
	v_mul_f32_e32 v64, v69, v71
	v_fmamk_f32 v69, v174, 0x3a000000, v150
	v_mul_f32_e32 v68, v68, v64
	v_mul_f32_e32 v64, v67, v70
	v_mul_f32_e32 v70, 0x4b800000, v69
	v_cmp_gt_f32_e32 vcc, s40, v69
	v_mul_f32_e32 v67, v66, v64
	v_cvt_pk_bf16_f32 v64, v80, v79
	v_cvt_pk_bf16_f32 v65, v76, v74
	v_cvt_pk_bf16_f32 v66, v72, v73
	v_mov_b32_e32 v72, v56
	v_cndmask_b32_e32 v69, v69, v70, vcc
	v_rsq_f32_e32 v70, v69
	v_mov_b32_e32 v73, v60
	v_mov_b32_e32 v60, v57
	v_cvt_pk_bf16_f32 v67, v68, v67
	v_mul_f32_e32 v71, 0x45800000, v70
	v_cndmask_b32_e32 v70, v70, v71, vcc
	v_pk_mul_f32 v[72:73], v[72:73], v[70:71] op_sel_hi:[1,0]
	v_mad_i64_i32 v[68:69], s[4:5], v122, s41, v[120:121]
	v_mul_f32_e32 v56, 0xbfb8aa3b, v73
	v_exp_f32_e32 v71, v56
	s_nop 0
	v_pk_mul_f32 v[56:57], v[60:61], v[70:71] op_sel_hi:[1,0]
	s_nop 0
	v_mul_f32_e32 v60, 0xbfb8aa3b, v57
	v_exp_f32_e32 v74, v60
	v_lshl_add_u64 v[60:61], v[68:69], 0, v[112:113]
	v_add_f32_e32 v68, 1.0, v71
	v_rcp_f32_e32 v68, v68
	global_store_dwordx4 v[60:61], v[64:67], off
	v_mov_b32_e32 v61, v62
	v_add_f32_e32 v69, 1.0, v74
	v_mul_f32_e32 v60, v73, v68
	v_mul_f32_e32 v64, v72, v60
	v_mov_b32_e32 v60, v58
	v_pk_mul_f32 v[60:61], v[60:61], v[70:71] op_sel_hi:[1,0]
	v_mov_b32_e32 v62, v59
	v_mul_f32_e32 v58, 0xbfb8aa3b, v61
	v_rcp_f32_e32 v69, v69
	v_exp_f32_e32 v65, v58
	v_pk_mul_f32 v[58:59], v[62:63], v[70:71] op_sel_hi:[1,0]
	v_mul_f32_e32 v57, v57, v69
	v_mul_f32_e32 v62, 0xbfb8aa3b, v59
	v_exp_f32_e32 v62, v62
	v_mul_f32_e32 v63, v56, v57
	v_add_f32_e32 v56, 1.0, v65
	v_rcp_f32_e32 v65, v56
	v_add_f32_e32 v56, 1.0, v62
	v_rcp_f32_e32 v62, v56
	v_mov_b32_e32 v56, v48
	v_mov_b32_e32 v57, v52
	v_pk_mul_f32 v[56:57], v[56:57], v[70:71] op_sel_hi:[1,0]
	v_mul_f32_e32 v52, v61, v65
	v_mul_f32_e32 v48, 0xbfb8aa3b, v57
	v_exp_f32_e32 v48, v48
	v_mul_f32_e32 v60, v60, v52
	v_mov_b32_e32 v52, v49
	v_mul_f32_e32 v59, v59, v62
	v_add_f32_e32 v48, 1.0, v48
	v_rcp_f32_e32 v61, v48
	v_pk_mul_f32 v[48:49], v[52:53], v[70:71] op_sel_hi:[1,0]
	v_mul_f32_e32 v58, v58, v59
	v_mul_f32_e32 v52, 0xbfb8aa3b, v49
	v_exp_f32_e32 v52, v52
	v_mul_f32_e32 v53, v57, v61
	v_mul_f32_e32 v56, v56, v53
	v_mov_b32_e32 v53, v54
	v_add_f32_e32 v52, 1.0, v52
	v_rcp_f32_e32 v57, v52
	v_mov_b32_e32 v52, v50
	v_pk_mul_f32 v[52:53], v[52:53], v[70:71] op_sel_hi:[1,0]
; __device__ __forceinline__ unsigned pk_bf16(float lo, float hi) { unsigned r; asm volatile("v_cvt_pk_bf16_f32 %0, %1, %2" : "=v"(r) : "v"(lo), "v"(hi)); return r; }
; __device__ __forceinline__ float sigmoidf_(float x) { return __builtin_amdgcn_rcpf(1.0f + __expf(-x)); }
;     __device__ __forceinline__ void operator()(const f32x4 (&acc)[2][2][4][2], const Unit& u, int wr, int wc, int fr, int fq) const {
;     ...
;         for (int ai = 0; ai < 2; ++ai)
; #pragma unroll
;             for (int m = 0; m < 4; ++m) {
;                 const int row = row0 + ai * 128 + m * 16;
;                 const float rstd = rsqrtf(rs[ai][m] * (1.0f / D) + RMS_EPS);
;                 f32x4 o[2];
; #pragma unroll
;                 for (int n = 0; n < 2; ++n)
; #pragma unroll
;                     for (int j = 0; j < 4; ++j) { const float gt = acc[ai][0][m][n][j] * rstd, up = acc[ai][1][m][n][j] * rstd; o[n][j] = gt * sigmoidf_(gt) * up; }
;                 u32x4 w; w.x = pk_bf16(o[0][0], o[0][1]); w.y = pk_bf16(o[0][2], o[0][3]); w.z = pk_bf16(o[1][0], o[1][1]); w.w = pk_bf16(o[1][2], o[1][3]);
;                 *(u32x4*)(U + (size_t)row * DFF + col0) = w;
	v_mov_b32_e32 v54, v51
	v_mul_f32_e32 v50, 0xbfb8aa3b, v53
	v_exp_f32_e32 v59, v50
	v_pk_mul_f32 v[50:51], v[54:55], v[70:71] op_sel_hi:[1,0]
	v_mul_f32_e32 v49, v49, v57
	v_mul_f32_e32 v54, 0xbfb8aa3b, v51
	v_exp_f32_e32 v54, v54
	v_add_f32_e32 v55, 1.0, v59
	v_rcp_f32_e32 v55, v55
	v_mul_f32_e32 v57, v48, v49
	v_add_f32_e32 v54, 1.0, v54
	v_rcp_f32_e32 v54, v54
	v_mul_f32_e32 v48, v53, v55
	v_fmamk_f32 v53, v153, 0x3a000000, v150
	v_mul_f32_e32 v52, v52, v48
	v_mul_f32_e32 v48, v51, v54
	v_mul_f32_e32 v54, 0x4b800000, v53
	v_cmp_gt_f32_e32 vcc, s40, v53
	v_mul_f32_e32 v51, v50, v48
	v_cvt_pk_bf16_f32 v48, v64, v63
	v_cvt_pk_bf16_f32 v49, v60, v58
	v_cvt_pk_bf16_f32 v50, v56, v57
	v_mov_b32_e32 v56, v40
	v_cndmask_b32_e32 v53, v53, v54, vcc
	v_rsq_f32_e32 v54, v53
	v_mov_b32_e32 v57, v44
	v_mov_b32_e32 v44, v41
	v_cvt_pk_bf16_f32 v51, v52, v51
	v_mul_f32_e32 v55, 0x45800000, v54
	v_cndmask_b32_e32 v54, v54, v55, vcc
	v_pk_mul_f32 v[56:57], v[56:57], v[54:55] op_sel_hi:[1,0]
	v_mad_i64_i32 v[52:53], s[4:5], v152, s41, v[120:121]
	v_mul_f32_e32 v40, 0xbfb8aa3b, v57
	v_exp_f32_e32 v55, v40
	s_nop 0
	v_pk_mul_f32 v[40:41], v[44:45], v[54:55] op_sel_hi:[1,0]
	s_nop 0
	v_mul_f32_e32 v44, 0xbfb8aa3b, v41
	v_exp_f32_e32 v58, v44
	v_lshl_add_u64 v[44:45], v[52:53], 0, v[112:113]
	v_add_f32_e32 v52, 1.0, v55
	v_rcp_f32_e32 v52, v52
	global_store_dwordx4 v[44:45], v[48:51], off
	v_mov_b32_e32 v45, v46
	v_add_f32_e32 v53, 1.0, v58
	v_mul_f32_e32 v44, v57, v52
	v_mul_f32_e32 v48, v56, v44
	v_mov_b32_e32 v44, v42
	v_pk_mul_f32 v[44:45], v[44:45], v[54:55] op_sel_hi:[1,0]
	v_mov_b32_e32 v46, v43
	v_mul_f32_e32 v42, 0xbfb8aa3b, v45
	v_rcp_f32_e32 v53, v53
	v_exp_f32_e32 v49, v42
	v_pk_mul_f32 v[42:43], v[46:47], v[54:55] op_sel_hi:[1,0]
	v_mul_f32_e32 v41, v41, v53
	v_mul_f32_e32 v46, 0xbfb8aa3b, v43
	v_exp_f32_e32 v46, v46
	v_mul_f32_e32 v47, v40, v41
	v_add_f32_e32 v40, 1.0, v49
	v_rcp_f32_e32 v49, v40
	v_add_f32_e32 v40, 1.0, v46
	v_rcp_f32_e32 v46, v40
	v_mov_b32_e32 v40, v32
	v_mov_b32_e32 v41, v36
	v_pk_mul_f32 v[40:41], v[40:41], v[54:55] op_sel_hi:[1,0]
	v_mul_f32_e32 v36, v45, v49
	v_mul_f32_e32 v32, 0xbfb8aa3b, v41
	v_exp_f32_e32 v32, v32
	v_mul_f32_e32 v44, v44, v36
	v_mov_b32_e32 v36, v33
	v_mul_f32_e32 v43, v43, v46
	v_add_f32_e32 v32, 1.0, v32
	v_rcp_f32_e32 v45, v32
	v_pk_mul_f32 v[32:33], v[36:37], v[54:55] op_sel_hi:[1,0]
	v_mul_f32_e32 v42, v42, v43
	v_mul_f32_e32 v36, 0xbfb8aa3b, v33
	v_exp_f32_e32 v36, v36
	v_mul_f32_e32 v37, v41, v45
	v_mul_f32_e32 v40, v40, v37
	v_mov_b32_e32 v37, v38
	v_add_f32_e32 v36, 1.0, v36
	v_rcp_f32_e32 v41, v36
	v_mov_b32_e32 v36, v34
	v_pk_mul_f32 v[36:37], v[36:37], v[54:55] op_sel_hi:[1,0]
	v_mov_b32_e32 v38, v35
	v_mul_f32_e32 v34, 0xbfb8aa3b, v37
	v_exp_f32_e32 v43, v34
	v_pk_mul_f32 v[34:35], v[38:39], v[54:55] op_sel_hi:[1,0]
	v_mul_f32_e32 v33, v33, v41
	v_mul_f32_e32 v38, 0xbfb8aa3b, v35
	v_exp_f32_e32 v38, v38
	v_add_f32_e32 v39, 1.0, v43
	v_rcp_f32_e32 v39, v39
	v_mul_f32_e32 v41, v32, v33
	v_add_f32_e32 v38, 1.0, v38
	v_rcp_f32_e32 v38, v38
	v_mul_f32_e32 v32, v37, v39
	v_fmamk_f32 v37, v151, 0x3a000000, v150
	v_mul_f32_e32 v36, v36, v32
	v_mul_f32_e32 v32, v35, v38
	v_mul_f32_e32 v38, 0x4b800000, v37
	v_cmp_gt_f32_e32 vcc, s40, v37
	v_mul_f32_e32 v35, v34, v32
	v_cvt_pk_bf16_f32 v32, v48, v47
	v_cvt_pk_bf16_f32 v33, v44, v42
	v_cvt_pk_bf16_f32 v34, v40, v41
	v_mov_b32_e32 v40, v24
	v_cndmask_b32_e32 v37, v37, v38, vcc
	v_rsq_f32_e32 v38, v37
	v_mov_b32_e32 v41, v28
	v_mov_b32_e32 v28, v25
	v_cvt_pk_bf16_f32 v35, v36, v35
	v_mul_f32_e32 v39, 0x45800000, v38
	v_cndmask_b32_e32 v38, v38, v39, vcc
	v_pk_mul_f32 v[40:41], v[40:41], v[38:39] op_sel_hi:[1,0]
	v_mad_i64_i32 v[36:37], s[4:5], v127, s41, v[120:121]
	v_mul_f32_e32 v24, 0xbfb8aa3b, v41
	v_exp_f32_e32 v39, v24
	s_nop 0
	v_pk_mul_f32 v[24:25], v[28:29], v[38:39] op_sel_hi:[1,0]
	s_nop 0
	v_mul_f32_e32 v28, 0xbfb8aa3b, v25
	v_exp_f32_e32 v42, v28
	v_lshl_add_u64 v[28:29], v[36:37], 0, v[112:113]
	v_add_f32_e32 v36, 1.0, v39
	v_rcp_f32_e32 v36, v36
	global_store_dwordx4 v[28:29], v[32:35], off
	v_mov_b32_e32 v29, v30
	v_add_f32_e32 v37, 1.0, v42
	v_mul_f32_e32 v28, v41, v36
	v_mul_f32_e32 v32, v40, v28
	v_mov_b32_e32 v28, v26
	v_pk_mul_f32 v[28:29], v[28:29], v[38:39] op_sel_hi:[1,0]
	v_mov_b32_e32 v30, v27
	v_mul_f32_e32 v26, 0xbfb8aa3b, v29
	v_rcp_f32_e32 v37, v37
	v_exp_f32_e32 v33, v26
	v_pk_mul_f32 v[26:27], v[30:31], v[38:39] op_sel_hi:[1,0]
; __device__ __forceinline__ unsigned pk_bf16(float lo, float hi) { unsigned r; asm volatile("v_cvt_pk_bf16_f32 %0, %1, %2" : "=v"(r) : "v"(lo), "v"(hi)); return r; }
; __device__ __forceinline__ float sigmoidf_(float x) { return __builtin_amdgcn_rcpf(1.0f + __expf(-x)); }
; #define PG8_WAIT_V(n) asm volatile("s_waitcnt vmcnt(" #n ")" ::: "memory")
; #define PG8_BAR __builtin_amdgcn_s_barrier()
; template <class Epi, class Sched>
; __device__ __forceinline__ void gemm_phase(LAS unsigned char* lds, const Gemm g, const Sched& S, const Epi& E) {
;     ...
;         if constexpr (!Epi::AFTER_DRAIN) E(acc, cur, wr, wc, fr, fq);
;         if (!has_next) break;
; #pragma unroll
;         for (int a = 0; a < 2; ++a)
; #pragma unroll
;             for (int b = 0; b < 2; ++b)
; #pragma unroll
;                 for (int m = 0; m < 4; ++m)
; #pragma unroll
;                     for (int n = 0; n < 2; ++n) acc[a][b][m][n] = (f32x4){0.f, 0.f, 0.f, 0.f};
;         cur = nxt; cA = nA; cB = nB; ++ui;
;     }
;     PG8_WAIT_V(0);
;     if (wr == 0) PG8_BAR;
;     __device__ __forceinline__ void operator()(const f32x4 (&acc)[2][2][4][2], const Unit& u, int wr, int wc, int fr, int fq) const {
;     ...
;         for (int ai = 0; ai < 2; ++ai)
; #pragma unroll
;             for (int m = 0; m < 4; ++m) {
;                 const int row = row0 + ai * 128 + m * 16;
;                 const float rstd = rsqrtf(rs[ai][m] * (1.0f / D) + RMS_EPS);
;                 f32x4 o[2];
; #pragma unroll
;                 for (int n = 0; n < 2; ++n)
; #pragma unroll
;                     for (int j = 0; j < 4; ++j) { const float gt = acc[ai][0][m][n][j] * rstd, up = acc[ai][1][m][n][j] * rstd; o[n][j] = gt * sigmoidf_(gt) * up; }
;                 u32x4 w; w.x = pk_bf16(o[0][0], o[0][1]); w.y = pk_bf16(o[0][2], o[0][3]); w.z = pk_bf16(o[1][0], o[1][1]); w.w = pk_bf16(o[1][2], o[1][3]);
;                 *(u32x4*)(U + (size_t)row * DFF + col0) = w;
	v_mul_f32_e32 v25, v25, v37
	v_mul_f32_e32 v30, 0xbfb8aa3b, v27
	v_exp_f32_e32 v30, v30
	v_mul_f32_e32 v31, v24, v25
	v_add_f32_e32 v24, 1.0, v33
	v_rcp_f32_e32 v33, v24
	v_add_f32_e32 v24, 1.0, v30
	v_rcp_f32_e32 v30, v24
	v_mov_b32_e32 v24, v16
	v_mov_b32_e32 v25, v20
	v_pk_mul_f32 v[24:25], v[24:25], v[38:39] op_sel_hi:[1,0]
	v_mul_f32_e32 v20, v29, v33
	v_mul_f32_e32 v16, 0xbfb8aa3b, v25
	v_exp_f32_e32 v16, v16
	v_mul_f32_e32 v28, v28, v20
	v_mov_b32_e32 v20, v17
	v_mul_f32_e32 v27, v27, v30
	v_add_f32_e32 v16, 1.0, v16
	v_rcp_f32_e32 v29, v16
	v_pk_mul_f32 v[16:17], v[20:21], v[38:39] op_sel_hi:[1,0]
	v_mul_f32_e32 v26, v26, v27
	v_mul_f32_e32 v20, 0xbfb8aa3b, v17
	v_exp_f32_e32 v20, v20
	v_mul_f32_e32 v21, v25, v29
	v_mul_f32_e32 v24, v24, v21
	v_mov_b32_e32 v21, v22
	v_add_f32_e32 v20, 1.0, v20
	v_rcp_f32_e32 v25, v20
	v_mov_b32_e32 v20, v18
	v_pk_mul_f32 v[20:21], v[20:21], v[38:39] op_sel_hi:[1,0]
	v_mov_b32_e32 v22, v19
	v_mul_f32_e32 v18, 0xbfb8aa3b, v21
	v_exp_f32_e32 v27, v18
	v_pk_mul_f32 v[18:19], v[22:23], v[38:39] op_sel_hi:[1,0]
	v_mul_f32_e32 v17, v17, v25
	v_mul_f32_e32 v22, 0xbfb8aa3b, v19
	v_exp_f32_e32 v22, v22
	v_add_f32_e32 v23, 1.0, v27
	v_rcp_f32_e32 v23, v23
	v_mul_f32_e32 v25, v16, v17
	v_add_f32_e32 v22, 1.0, v22
	v_rcp_f32_e32 v22, v22
	v_mul_f32_e32 v16, v21, v23
	v_fmamk_f32 v21, v126, 0x3a000000, v150
	v_mul_f32_e32 v20, v20, v16
	v_mul_f32_e32 v16, v19, v22
	v_mul_f32_e32 v22, 0x4b800000, v21
	v_cmp_gt_f32_e32 vcc, s40, v21
	v_mul_f32_e32 v19, v18, v16
	v_cvt_pk_bf16_f32 v16, v32, v31
	v_cvt_pk_bf16_f32 v17, v28, v26
	v_cvt_pk_bf16_f32 v18, v24, v25
	v_mov_b32_e32 v24, v8
	v_cndmask_b32_e32 v21, v21, v22, vcc
	v_rsq_f32_e32 v22, v21
	v_mov_b32_e32 v25, v12
	v_mov_b32_e32 v12, v9
	v_cvt_pk_bf16_f32 v19, v20, v19
	v_mul_f32_e32 v23, 0x45800000, v22
	v_cndmask_b32_e32 v22, v22, v23, vcc
	v_pk_mul_f32 v[24:25], v[24:25], v[22:23] op_sel_hi:[1,0]
	v_mad_i64_i32 v[20:21], s[4:5], v125, s41, v[120:121]
	v_mul_f32_e32 v8, 0xbfb8aa3b, v25
	v_exp_f32_e32 v23, v8
	s_and_b64 vcc, exec, s[0:1]
	v_pk_mul_f32 v[8:9], v[12:13], v[22:23] op_sel_hi:[1,0]
	s_nop 0
	v_mul_f32_e32 v12, 0xbfb8aa3b, v9
	v_exp_f32_e32 v26, v12
	v_lshl_add_u64 v[12:13], v[20:21], 0, v[112:113]
	v_add_f32_e32 v20, 1.0, v23
	v_rcp_f32_e32 v20, v20
	global_store_dwordx4 v[12:13], v[16:19], off
	v_mov_b32_e32 v13, v14
	v_add_f32_e32 v21, 1.0, v26
	v_mul_f32_e32 v12, v25, v20
	v_mul_f32_e32 v16, v24, v12
	v_mov_b32_e32 v12, v10
	v_pk_mul_f32 v[12:13], v[12:13], v[22:23] op_sel_hi:[1,0]
	v_mov_b32_e32 v14, v11
	v_mul_f32_e32 v10, 0xbfb8aa3b, v13
	v_rcp_f32_e32 v21, v21
	v_exp_f32_e32 v17, v10
	v_pk_mul_f32 v[10:11], v[14:15], v[22:23] op_sel_hi:[1,0]
	v_mul_f32_e32 v9, v9, v21
	v_mul_f32_e32 v14, 0xbfb8aa3b, v11
	v_exp_f32_e32 v14, v14
	v_mul_f32_e32 v15, v8, v9
	v_add_f32_e32 v8, 1.0, v17
	v_rcp_f32_e32 v17, v8
	v_add_f32_e32 v8, 1.0, v14
	v_rcp_f32_e32 v14, v8
	v_mov_b32_e32 v8, v0
	v_mov_b32_e32 v9, v4
	v_pk_mul_f32 v[8:9], v[8:9], v[22:23] op_sel_hi:[1,0]
	v_mul_f32_e32 v4, v13, v17
	v_mul_f32_e32 v0, 0xbfb8aa3b, v9
	v_exp_f32_e32 v0, v0
	v_mul_f32_e32 v12, v12, v4
	v_mov_b32_e32 v4, v1
	v_mul_f32_e32 v11, v11, v14
	v_add_f32_e32 v0, 1.0, v0
	v_rcp_f32_e32 v13, v0
	v_pk_mul_f32 v[0:1], v[4:5], v[22:23] op_sel_hi:[1,0]
	v_mul_f32_e32 v10, v10, v11
	v_mul_f32_e32 v4, 0xbfb8aa3b, v1
	v_exp_f32_e32 v4, v4
	v_mul_f32_e32 v5, v9, v13
	v_mul_f32_e32 v8, v8, v5
	v_mov_b32_e32 v5, v6
	v_add_f32_e32 v4, 1.0, v4
	v_rcp_f32_e32 v9, v4
	v_mov_b32_e32 v4, v2
	v_pk_mul_f32 v[4:5], v[4:5], v[22:23] op_sel_hi:[1,0]
	v_mov_b32_e32 v6, v3
	v_mul_f32_e32 v2, 0xbfb8aa3b, v5
	v_exp_f32_e32 v11, v2
	v_pk_mul_f32 v[2:3], v[6:7], v[22:23] op_sel_hi:[1,0]
	v_mul_f32_e32 v1, v1, v9
	v_mul_f32_e32 v6, 0xbfb8aa3b, v3
	v_exp_f32_e32 v6, v6
	v_add_f32_e32 v7, 1.0, v11
	v_rcp_f32_e32 v7, v7
	v_mul_f32_e32 v9, v0, v1
	v_add_f32_e32 v6, 1.0, v6
	v_rcp_f32_e32 v6, v6
	v_mul_f32_e32 v0, v5, v7
	v_mul_f32_e32 v4, v4, v0
	v_mul_f32_e32 v0, v3, v6
	v_mul_f32_e32 v3, v2, v0
	v_cvt_pk_bf16_f32 v0, v16, v15
	v_cvt_pk_bf16_f32 v1, v12, v10
	v_cvt_pk_bf16_f32 v2, v8, v9
	v_cvt_pk_bf16_f32 v3, v4, v3
	v_mad_i64_i32 v[4:5], s[4:5], v123, s41, v[120:121]
	v_lshl_add_u64 v[4:5], v[4:5], 0, v[112:113]
	global_store_dwordx4 v[4:5], v[0:3], off
	s_cbranch_vccz .LBB0_1202
	s_nop 0
	s_nop 0
	s_nop 0
	s_nop 0
	s_nop 0
	s_nop 0
	s_nop 0
	s_nop 0
	s_waitcnt vmcnt(0)
	s_cmpk_gt_u32 s14, 0xff
	s_cbranch_scc1 .LBB0_1213
	s_barrier
